# c6 plus one static s_setprio 1 for waves 4-7 for the duration of a C unit
# speedup vs baseline: 1.0122x; 1.0122x over previous
; template <int MODE>
; DI void attn_unit(unsigned char* lds, const AttnParams& ap, int b, int h, int qb, int tid) {
;     ...
;   const int wave = tid >> 6, lane = tid & 63, r32 = lane & 31, hi = lane >> 5, bh = b * 4 + h;
;   constexpr int qcol0 = (MODE == 0) ? C_AQ : (MODE == 1) ? C_CQ : C_DQ, kcol0 = (MODE == 0) ? C_AK : (MODE == 1) ? C_CK : C_DK, ycol0 = (MODE == 0) ? 0 : (MODE == 1) ? 512 : 768;
;   const bf16_t* Vt = ap.Vt + (size_t)((MODE == 0) ? 0 : (MODE == 1) ? 2 : 3) * T_ * 256;
;   const size_t tokb = (size_t)b * SEQ;
;   const int qpos = qb * 256 + wave * 32 + r32, cw = qb * 4 + (wave >> 1);
;   bf16x8 qf[4];
;   { const bf16_t* qp = ap.P + (tokb + qpos) * PLD + qcol0 + h * 64 + 8 * hi;
; #pragma unroll
;     for (int ks = 0; ks < 4; ++ks) qf[ks] = *(const bf16x8*)(qp + 16 * ks); }
;   bf16_t* Ks0 = (bf16_t*)lds; bf16_t* Vs0 = Ks0 + NCH * 64 * 72; volatile int* flags = (volatile int*)(lds + 2 * NCH * 64 * 72 * 2);
;   const int jhi = 4 * qb + 3, jlo = (MODE == 0) ? ((4 * qb - 8 > 0) ? 4 * qb - 8 : 0) : 0, ntiles = jhi - jlo + 1;
;   const int lrow = tid >> 3, lch = tid & 7;
;   const bf16_t* kg = ap.P + (tokb + lrow) * PLD + kcol0 + h * 64 + 8 * lch;
;   const bf16_t* vg = Vt + (size_t)bh * 256 * 4096 + lrow * 64 + 8 * lch;
;   const int j0 = (MODE == 2) ? jhi : jlo;
;   u32x4 kreg[NCH], vreg[NCH];
; #pragma unroll
;   for (int c = 0; c < NCH; ++c) { const int jc = (MODE == 2) ? j0 - c : j0 + c; kreg[c] = *(const u32x4*)(kg + (size_t)jc * 64 * PLD); vreg[c] = *(const u32x4*)(vg + (size_t)jc * 4096); }
;   f32x16 O0[2], O1[2]; float l0 = 0.f, l1 = 0.f, cum = 0.f;
; #pragma unroll
;   for (int eb = 0; eb < 2; ++eb) { O0[eb] = splat16(0.f); O1[eb] = splat16(0.f); }
;   bool wdone = false;
;   if (MODE == 2 && D_EARLY) { if (tid < 8) flags[tid] = 0; }
;   for (int n = 0; n < ntiles; n += NCH) {
;     const int jb = (MODE == 2) ? jhi - n : jlo + n;
;     __syncthreads();
;     if (MODE == 2 && D_EARLY) { int alld = 1;
; #pragma unroll
;       for (int w = 0; w < 8; ++w) alld &= flags[w];
;       if (alld) break; }
; #pragma unroll
;     for (int c = 0; c < NCH; ++c) { *(u32x4*)(Ks0 + (c * 64 + lrow) * 72 + 8 * lch) = kreg[c]; *(u32x4*)(Vs0 + (c * 64 + lrow) * 72 + 8 * lch) = vreg[c]; }
;     __syncthreads();
;     if (n + NCH < ntiles) {
; #pragma unroll
.LBB0_845:
	v_readlane_b32 s0, v255, 51
	v_readlane_b32 s1, v255, 52
	s_andn2_saveexec_b64 s[6:7], s[0:1]
	s_cbranch_execz .LBB0_853
	v_mov_b32_e32 v1, v156
	v_readlane_b32 s0, v255, 25
	v_ashrrev_i32_e32 v2, 1, v1
	v_and_b32_e32 v2, 0xffffffe0, v2
	v_and_b32_e32 v7, 31, v1
	v_lshl_add_u32 v2, v0, 8, v2
	v_or_b32_e32 v2, v2, v7
	v_lshlrev_b32_e32 v32, 14, v4
	v_ashrrev_i32_e32 v3, 31, v2
	v_readlane_b32 s1, v255, 26
	v_lshl_add_u64 v[134:135], v[2:3], 0, v[32:33]
	v_bfe_u32 v47, v1, 5, 1
	v_mov_b64_e32 v[2:3], s[0:1]
	v_mad_u64_u32 v[8:9], s[0:1], v134, s82, v[2:3]
	v_mad_i32_i24 v9, v135, s82, v9
	v_lshlrev_b32_e32 v10, 7, v5
	v_mov_b32_e32 v11, v33
	v_lshl_add_u64 v[8:9], v[8:9], 0, v[10:11]
	v_lshlrev_b32_e32 v132, 4, v47
	v_mov_b32_e32 v133, v33
	v_lshl_add_u64 v[8:9], v[8:9], 0, v[132:133]
	v_ashrrev_i32_e32 v14, 3, v1
	global_load_dwordx4 v[112:115], v[8:9], off offset:3584
	global_load_dwordx4 v[42:45], v[8:9], off offset:3616
	global_load_dwordx4 v[38:41], v[8:9], off offset:3648
	global_load_dwordx4 v[34:37], v[8:9], off offset:3680
	v_add_u32_e32 v8, v14, v32
	v_mad_i64_i32 v[2:3], s[0:1], v8, s82, v[2:3]
	v_lshlrev_b32_e32 v8, 4, v1
	v_and_b32_e32 v32, 0x70, v8
	v_lshlrev_b32_e32 v8, 21, v5
	v_readlane_b32 s0, v255, 41
	v_lshl_add_u64 v[2:3], v[2:3], 0, v[10:11]
	v_lshl_or_b32 v8, v4, 23, v8
	v_mov_b32_e32 v9, v33
	v_readlane_b32 s1, v255, 42
	v_lshlrev_b32_e32 v12, 6, v14
	v_lshl_add_u64 v[2:3], v[2:3], 0, v[32:33]
	v_lshl_add_u64 v[10:11], s[0:1], 0, v[8:9]
	v_ashrrev_i32_e32 v13, 31, v12
	s_movk_i32 s0, 0x1000
	v_lshlrev_b64 v[12:13], 1, v[12:13]
	v_add_co_u32_e32 v2, vcc, s0, v2
	v_lshl_add_u64 v[10:11], v[10:11], 0, v[12:13]
	s_nop 0
	v_addc_co_u32_e32 v3, vcc, 0, v3, vcc
	v_lshl_add_u64 v[10:11], v[10:11], 0, v[32:33]
	global_load_dwordx4 v[120:123], v[2:3], off
	global_load_dwordx4 v[116:119], v[10:11], off
	v_ashrrev_i32_e32 v157, 7, v1
	v_lshlrev_b32_e32 v0, 2, v0
	v_mul_lo_u32 v1, v14, s68
	v_or_b32_e32 v12, v12, v32
	v_readlane_b32 s0, v255, 47
	v_add_u32_e32 v191, v157, v0
	v_add3_u32 v190, 0, v32, v1
	v_or_b32_e32 v192, 3, v0
	v_lshl_add_u64 v[0:1], v[12:13], 0, v[8:9]
	v_readlane_b32 s1, v255, 48
	v_add_u16_e32 v2, -1, v6
	v_and_b32_e32 v2, 3, v2
	v_lshl_add_u64 v[136:137], s[0:1], 0, v[0:1]
	v_mad_i64_i32 v[0:1], s[0:1], v14, s82, 0
	s_mov_b32 s0, 0x6880000
	s_nop 0
	v_mad_u64_u32 v[0:1], s[0:1], v4, s0, v[0:1]
	v_lshlrev_b32_e32 v2, 7, v2
	v_mov_b32_e32 v3, v33
	v_lshl_add_u64 v[0:1], v[0:1], 0, v[2:3]
	v_readlane_b32 s0, v255, 49
	v_lshl_add_u64 v[0:1], v[0:1], 0, v[32:33]
	v_readlane_b32 s1, v255, 50
	v_mov_b32_e32 v14, v33
	v_mov_b32_e32 v15, v33
	v_lshlrev_b32_e32 v46, 6, v5
	v_mul_u32_u24_e32 v155, 0x90, v7
	v_lshl_add_u64 v[138:139], s[0:1], 0, v[0:1]
	v_mov_b32_e32 v32, v33
	v_mov_b32_e32 v0, v33
	v_mov_b32_e32 v1, v33
	v_mov_b32_e32 v2, v33
	v_mov_b32_e32 v4, v33
	v_mov_b32_e32 v5, v33
	v_mov_b32_e32 v6, v33
	v_mov_b32_e32 v7, v33
	v_mov_b32_e32 v8, v33
	v_mov_b32_e32 v10, v33
	v_mov_b32_e32 v11, v33
	v_mov_b32_e32 v12, v33
	v_mov_b32_e32 v13, v33
	v_mov_b64_e32 v[78:79], v[14:15]
	v_mov_b64_e32 v[30:31], v[14:15]
	v_mov_b64_e32 v[94:95], v[14:15]
	s_mov_b32 s4, 0
	v_add_u32_e32 v133, 0, v132
	s_mov_b64 s[0:1], 0
	v_mov_b64_e32 v[76:77], v[12:13]
	v_mov_b64_e32 v[74:75], v[10:11]
	v_mov_b64_e32 v[72:73], v[8:9]
	v_mov_b64_e32 v[70:71], v[6:7]
	v_mov_b64_e32 v[68:69], v[4:5]
	v_mov_b64_e32 v[66:67], v[2:3]
	v_mov_b64_e32 v[64:65], v[0:1]
	v_mov_b64_e32 v[28:29], v[12:13]
	v_mov_b64_e32 v[26:27], v[10:11]
	v_mov_b64_e32 v[24:25], v[8:9]
	v_mov_b64_e32 v[22:23], v[6:7]
	v_mov_b64_e32 v[20:21], v[4:5]
	v_mov_b64_e32 v[18:19], v[2:3]
	v_mov_b64_e32 v[16:17], v[0:1]
	v_mov_b64_e32 v[92:93], v[12:13]
	v_mov_b64_e32 v[90:91], v[10:11]
	v_mov_b64_e32 v[88:89], v[8:9]
	v_mov_b64_e32 v[86:87], v[6:7]
	v_mov_b64_e32 v[84:85], v[4:5]
	v_mov_b64_e32 v[82:83], v[2:3]
	v_mov_b64_e32 v[80:81], v[0:1]
	v_mov_b64_e32 v[140:141], v[32:33]
	v_readfirstlane_b32 s5, v191
	v_readfirstlane_b32 s8, v192
	v_readfirstlane_b32 s2, v138
	v_readfirstlane_b32 s3, v139
	v_readfirstlane_b32 s10, v136
	v_readfirstlane_b32 s11, v137
	v_readfirstlane_b32 s0, v156
	s_nop 3
	s_cmp_ge_u32 s0, 256
	s_cbranch_scc0 .Lc_noprio
	s_setprio 1
.Lc_noprio:
	v_and_b32_e32 v204, 7, v156
	v_bfe_u32 v205, v156, 4, 3
	v_xor_b32_e32 v205, v204, v205
	v_sub_u32_e32 v206, v205, v204
	v_lshlrev_b32_e32 v206, 4, v206
	v_subrev_u32_e32 v32, s2, v138
	v_subrev_u32_e32 v157, s10, v136
	v_add_u32_e32 v32, v32, v206
	v_add_u32_e32 v157, v157, v206
	v_lshrrev_b32_e32 v207, 3, v156
	v_lshlrev_b32_e32 v207, 7, v207
	v_lshl_add_u32 v207, v205, 4, v207
	v_and_b32_e32 v204, 31, v156
	v_bfe_u32 v205, v156, 5, 1
	v_bfe_u32 v206, v156, 1, 3
	v_lshlrev_b32_e32 v204, 7, v204
	v_add_u32_e32 v146, 0, v205
	v_xor_b32_e32 v146, v146, v206
	v_lshl_add_u32 v146, v146, 4, v204
	v_add_u32_e32 v147, 2, v205
	v_xor_b32_e32 v147, v147, v206
	v_lshl_add_u32 v147, v147, 4, v204
	v_add_u32_e32 v148, 4, v205
	v_xor_b32_e32 v148, v148, v206
	v_lshl_add_u32 v148, v148, 4, v204
	v_add_u32_e32 v149, 6, v205
	v_xor_b32_e32 v149, v149, v206
	v_lshl_add_u32 v149, v149, 4, v204
	s_lshr_b32 s0, s0, 6
	s_lshl_b32 s0, s0, 10
	s_add_i32 m0, s0, 16384
	s_add_i32 s4, s4, 1
	global_load_lds_dwordx4 v32, s[2:3]
	s_add_i32 m0, s0, 24576
	s_add_u32 s2, s2, 0x68800
	s_addc_u32 s3, s3, 0
	global_load_lds_dwordx4 v157, s[10:11]
	s_add_u32 s10, s10, 0x2000
	s_addc_u32 s11, s11, 0
	s_waitcnt vmcnt(2)
	ds_write_b128 v207, v[120:123]
	ds_write_b128 v207, v[116:119] offset:8192
	s_waitcnt vmcnt(0) lgkmcnt(0)
	s_barrier
	ds_read_b128 v[166:169], v146
	ds_read_b128 v[170:173], v147
	v_mov_b32_e32 v158, 0
	v_mov_b32_e32 v159, 0
	v_mov_b32_e32 v160, 0
	v_mov_b32_e32 v161, 0
	v_mov_b32_e32 v162, 0
	v_mov_b32_e32 v163, 0
	v_mov_b32_e32 v164, 0
	v_mov_b32_e32 v165, 0
	v_mov_b32_e32 v150, 0
	v_mov_b32_e32 v151, 0
	s_mov_b32 s4, 0
	s_waitcnt lgkmcnt(0)
	v_mfma_f32_32x32x16_bf16 v[96:111], v[166:169], v[112:115], v[48:63]
	v_mfma_f32_32x32x16_bf16 v[96:111], v[170:173], v[42:45], v[96:111]
	ds_read_b128 v[166:169], v148
	ds_read_b128 v[170:173], v149
	v_mov_b32_e32 v174, 0
	v_mov_b32_e32 v175, 0
	v_mov_b32_e32 v176, 0
	v_mov_b32_e32 v177, 0
	v_mov_b32_e32 v178, 0
	v_mov_b32_e32 v179, 0
	v_mov_b32_e32 v180, 0
	v_mov_b32_e32 v181, 0
	v_mov_b32_e32 v182, 0
	v_mov_b32_e32 v183, 0
	v_mov_b32_e32 v184, 0
	v_mov_b32_e32 v185, 0
	v_mov_b32_e32 v186, 0
	v_mov_b32_e32 v187, 0
	v_mov_b32_e32 v188, 0
	v_mov_b32_e32 v189, 0

; template <int MODE>
; DI void attn_unit(unsigned char* lds, const AttnParams& ap, int b, int h, int qb, int tid) {
;     ...
;   } else if (MODE == 1) { l0 += __shfl_xor(l0, 32); l1 += __shfl_xor(l1, 32); const float i0 = 1.0f / l0, i1 = ap.lam / l1; float ss = 0.f;
.Lc_tiles_done:
	v_add_f32_e32 v141, v141, v150
	v_add_f32_e32 v140, v140, v151
	s_setprio 0
	s_mov_b64 s[0:1], exec
